# attention: per-tile max chain removed; tile consumed with current softmax reference, rare post-hoc rescale (power-of-two factor) when a row's tile sum exceeds 2^13
# speedup vs baseline: 1.0135x; 1.0135x over previous
; #define LAS __attribute__((address_space(3)))
; DI int tid_now(int ws_) { int l; asm volatile("v_mbcnt_lo_u32_b32 %0, -1, 0\n\tv_mbcnt_hi_u32_b32 %0, -1, %0" : "=v"(l)); return ws_ * 64 + l; }
; DI void attn_prompt_item(const __attribute__((address_space(4))) Args& a, LAS unsigned char* lds, int ws_, int b, int h, int qt, float lam, bool dry = false) {
;     ...
;     const int tid = tid_now(ws_);
;     const int wave = ws_, lane = tid & 63, qs = wave >> 1, map = wave & 1;
;     const bf16* Qb = (const bf16*)(a.ws + WS_QB); const bf16* Kg = (const bf16*)(a.ws + WS_KB); const bf16* Vg = (const bf16*)(a.ws + WS_VT);
;     const int rb = b * 8192, q0 = qt * 128;
;     const int qrow = rb + q0 + qs * 32 + (lane & 31);
;     bf16x8 Q[4];
; #pragma unroll
;     for (int ds = 0; ds < 4; ++ds) Q[ds] = *(const bf16x8*)(Qb + (size_t)qrow * 1024 + h * 128 + map * 64 + ds * 16 + (lane >> 5) * 8);
;     f32x16 O[4];
; #pragma unroll
;     for (int dt = 0; dt < 4; ++dt)
; #pragma unroll
;         for (int i = 0; i < 16; ++i) O[dt][i] = 0.f;
;     float m = -1e30f, l = 0.f;
;     const int nt = 2 * qt + 2, my_nt = qs < 2 ? nt - 1 : nt;
;     const bf16* ksrc[2]; const bf16* vsrc[2]; int kdst[2], vdst[2];
; #pragma unroll
;     for (int i = 0; i < 2; ++i) {
;         const int id = tid + 512 * i;
;         ksrc[i] = Kg + (size_t)(rb + (id >> 4)) * 1024 + h * 128 + (id & 15) * 8; kdst[i] = (id >> 4) * 272 + (id & 15) * 16;
;         vsrc[i] = Vg + ((size_t)(b * 8 + h) * 128 + (id >> 3)) * 8192 + (id & 7) * 8; vdst[i] = KT_BYTES + (id >> 3) * 144 + (id & 7) * 16;
;     }
;     v4u kx[2], vx[2];
; #pragma unroll
;     for (int i = 0; i < 2; ++i) { kx[i] = *(const v4u*)(ksrc[i]); vx[i] = *(const v4u*)(vsrc[i]); }
; #pragma unroll
;     for (int i = 0; i < 2; ++i) { *(LAS v4u*)(lds + kdst[i]) = kx[i]; *(LAS v4u*)(lds + vdst[i]) = vx[i]; }
;     __syncthreads();
.LBB0_1426:
	s_or_b64 exec, exec, s[4:5]
	s_waitcnt lgkmcnt(0)
	s_barrier
	ds_read_b32 v0, v150
	s_movk_i32 s4, 0xaff
	s_waitcnt lgkmcnt(0)
	s_barrier
	v_cmp_lt_i32_e32 vcc, s4, v0
	v_readfirstlane_b32 s93, v0
	s_mov_b64 s[4:5], -1
	s_cbranch_vccnz .LBB0_1421
	s_cmpk_gt_i32 s93, 0x7f
	s_cbranch_scc0 .LBB0_1510
	s_cmpk_gt_u32 s93, 0x27f
	s_cbranch_scc0 .LBB0_1470
	s_cmpk_gt_u32 s93, 0x2ff
	s_cbranch_scc0 .LBB0_1445
	s_add_i32 s4, s93, 0xfffffd00
	s_lshr_b32 s34, s4, 5
	s_bfe_u32 s35, s93, 0x20003
	s_sub_i32 s7, 63, s34
	s_lshl_b32 s9, s35, 13
	s_lshl_b32 s6, s7, 7
	s_add_i32 s8, s9, s87
	s_add_i32 s8, s8, s6
	s_lshl_b32 s6, s93, 7
	s_load_dwordx2 s[4:5], s[20:21], 0x70
	v_mbcnt_lo_u32_b32 v151, -1, 0
	v_mbcnt_hi_u32_b32 v151, -1, v151
	s_and_b32 s6, s6, 0x380
	v_add_u32_e32 v8, s76, v151
	v_and_b32_e32 v23, 31, v151
	s_lshl_b32 s7, s7, 1
	v_or_b32_e32 v96, s8, v23
	s_lshl_b32 s24, s6, 1
	s_lshl_b32 s8, s88, 1
	s_add_i32 s70, s7, 2
	s_or_b32 s7, s7, 1
	v_add_u32_e32 v10, 0x200, v8
	v_lshlrev_b64 v[0:1], 11, v[96:97]
	s_add_u32 s10, s85, s24
	v_lshlrev_b32_e32 v2, 4, v151
	v_ashrrev_i32_e32 v22, 4, v8
	v_ashrrev_i32_e32 v28, 4, v10
	v_lshl_add_u64 v[0:1], s[38:39], 0, v[0:1]
	s_addc_u32 s11, s86, 0
	v_and_b32_e32 v18, 0xf0, v2
	v_mov_b32_e32 v19, v97
	v_add_u32_e32 v4, s9, v22
	v_ashrrev_i32_e32 v24, 3, v8
	v_add_u32_e32 v8, s9, v28
	v_lshl_add_u64 v[16:17], v[0:1], 0, s[24:25]
	v_lshl_add_u64 v[0:1], s[10:11], 0, v[18:19]
	s_lshl_b32 s10, s35, 10
	v_ashrrev_i32_e32 v5, 31, v4
	v_ashrrev_i32_e32 v9, 31, v8
	v_ashrrev_i32_e32 v30, 3, v10
	s_or_b32 s24, s10, s6
	v_lshlrev_b64 v[4:5], 11, v[4:5]
	v_ashrrev_i32_e32 v25, 31, v24
	v_lshlrev_b64 v[8:9], 11, v[8:9]
	v_ashrrev_i32_e32 v31, 31, v30
	v_and_b32_e32 v20, 0x70, v2
	v_mov_b32_e32 v21, v97
	v_lshl_add_u64 v[4:5], v[0:1], 0, v[4:5]
	v_lshl_add_u64 v[6:7], v[24:25], 0, s[24:25]
	v_lshl_add_u64 v[8:9], v[0:1], 0, v[8:9]
	v_lshl_add_u64 v[0:1], v[30:31], 0, s[24:25]
	v_lshl_add_u64 v[2:3], s[40:41], 0, v[20:21]
	v_lshlrev_b64 v[26:27], 14, v[6:7]
	v_lshlrev_b64 v[32:33], 14, v[0:1]
	v_lshl_add_u64 v[6:7], v[2:3], 0, v[26:27]
	v_lshl_add_u64 v[12:13], v[2:3], 0, v[32:33]
	global_load_dwordx4 v[0:3], v[4:5], off
	s_nop 0
	global_load_dwordx4 v[4:7], v[6:7], off
	s_nop 0
	global_load_dwordx4 v[8:11], v[8:9], off
	s_nop 0
	global_load_dwordx4 v[12:15], v[12:13], off
	s_mov_b32 s9, s25
	v_lshrrev_b32_e32 v19, 1, v151
	v_lshl_add_u64 v[16:17], v[16:17], 0, s[8:9]
	v_and_b32_e32 v130, 16, v19
	v_mov_b32_e32 v131, v97
	v_lshl_add_u64 v[16:17], v[16:17], 0, v[130:131]
	global_load_dwordx4 v[110:113], v[16:17], off
	global_load_dwordx4 v[106:109], v[16:17], off offset:32
	global_load_dwordx4 v[102:105], v[16:17], off offset:64
	global_load_dwordx4 v[98:101], v[16:17], off offset:96
	v_mad_u64_u32 v[132:133], s[8:9], v22, s77, v[18:19]
	v_mad_u64_u32 v[134:135], s[8:9], v24, s78, v[20:21]
	v_mad_u64_u32 v[136:137], s[8:9], v28, s77, v[18:19]
	v_mad_u64_u32 v[138:139], s[8:9], v30, s78, v[20:21]
	s_and_b64 s[8:9], s[42:43], exec
	s_cselect_b32 s7, s7, s70
	s_lshl_b32 s8, s34, 1
	v_and_b32_e32 v131, 63, v151
	v_add_u32_e32 v17, 0, v132
	s_sub_i32 s8, 0x7f, s8
	s_lshl_b32 s9, s35, 24
	v_add_u32_e32 v19, 0, v134
	v_add_u32_e32 v21, 0, v136
	v_add_u32_e32 v24, 0, v138
	s_add_u32 s10, s9, 0x1f121000
	v_ashrrev_i32_e32 v29, 31, v28
	v_mul_u32_u24_e32 v153, 0x110, v23
	v_mul_u32_u24_e32 v139, 0x90, v23
	s_addc_u32 s11, 0, 0
	v_ashrrev_i32_e32 v23, 31, v22
	s_lshl_b32 s9, s93, 8
	v_or_b32_e32 v16, 32, v131
	v_or_b32_e32 v32, v32, v20
	v_or_b32_e32 v26, v26, v20
	s_and_b32 s9, s9, 0x700
	v_mov_b32_e32 v48, v97
	v_mov_b32_e32 v49, v97
	s_waitcnt vmcnt(7)
	ds_write_b128 v17, v[0:3]
	s_waitcnt vmcnt(6)
	ds_write_b128 v19, v[4:7] offset:17408
	s_waitcnt vmcnt(5)
	ds_write_b128 v21, v[8:11]
	s_waitcnt vmcnt(4)
	ds_write_b128 v24, v[12:15] offset:17408
	v_or_b32_e32 v0, 0x60, v131
	v_mul_u32_u24_e32 v135, 0x90, v0
	v_lshlrev_b64 v[0:1], 11, v[28:29]
	v_lshl_add_u64 v[144:145], s[10:11], 0, v[0:1]
	v_lshlrev_b64 v[0:1], 11, v[22:23]
	v_lshl_add_u64 v[146:147], s[10:11], 0, v[0:1]
	v_mul_u32_u24_e32 v154, 0x110, v16
	v_mul_u32_u24_e32 v137, 0x90, v16
	v_lshl_add_u64 v[140:141], v[32:33], 0, s[26:27]
	v_lshl_add_u64 v[142:143], v[26:27], 0, s[26:27]
	v_or3_b32 v144, v144, s9, v18
	v_or3_b32 v146, v146, s9, v18
	v_mov_b32_e32 v50, v97
	v_mov_b32_e32 v51, v97
	v_mov_b32_e32 v52, v97
	v_mov_b32_e32 v53, v97
	v_mov_b32_e32 v54, v97
	v_mov_b32_e32 v55, v97
	v_mov_b32_e32 v56, v97
	v_mov_b32_e32 v57, v97
	v_mov_b32_e32 v58, v97
	v_mov_b32_e32 v59, v97
	v_mov_b32_e32 v60, v97
	v_mov_b32_e32 v61, v97
	v_mov_b32_e32 v62, v97
	v_mov_b32_e32 v63, v97
	v_mov_b64_e32 v[32:33], v[48:49]
	v_mov_b64_e32 v[16:17], v[48:49]
	v_mov_b64_e32 v[0:1], v[48:49]
	s_mov_b32 s9, 0
	v_mov_b32_e32 v152, 0x41000000
	v_mov_b32_e32 v209, 0
	v_mov_b32_e32 v192, 0
	v_mov_b32_e32 v193, 0
	v_mov_b32_e32 v194, 0
	v_mov_b32_e32 v195, 0
	v_mov_b32_e32 v196, 0
	v_mov_b32_e32 v197, 0
	v_mov_b32_e32 v198, 0
	v_mov_b32_e32 v199, 0
	v_mov_b32_e32 v200, 0
	v_mov_b32_e32 v201, 0
	v_mov_b32_e32 v202, 0
	v_mov_b32_e32 v203, 0
	v_mov_b32_e32 v204, 0
	v_mov_b32_e32 v205, 0
	v_mov_b32_e32 v206, 0
	v_mov_b32_e32 v207, 0
	v_mov_b32_e32 v133, 0
	v_mov_b64_e32 v[34:35], v[50:51]
	v_mov_b64_e32 v[36:37], v[52:53]
	v_mov_b64_e32 v[38:39], v[54:55]
	v_mov_b64_e32 v[40:41], v[56:57]
	v_mov_b64_e32 v[42:43], v[58:59]
	v_mov_b64_e32 v[44:45], v[60:61]
	v_mov_b64_e32 v[46:47], v[62:63]
	v_mov_b64_e32 v[18:19], v[50:51]
	v_mov_b64_e32 v[20:21], v[52:53]
	v_mov_b64_e32 v[22:23], v[54:55]
	v_mov_b64_e32 v[24:25], v[56:57]
	v_mov_b64_e32 v[26:27], v[58:59]
	v_mov_b64_e32 v[28:29], v[60:61]
	v_mov_b64_e32 v[30:31], v[62:63]
	v_mov_b64_e32 v[2:3], v[50:51]
	v_mov_b64_e32 v[4:5], v[52:53]
	v_mov_b64_e32 v[6:7], v[54:55]
	v_mov_b64_e32 v[8:9], v[56:57]
	v_mov_b64_e32 v[10:11], v[58:59]
	v_mov_b64_e32 v[12:13], v[60:61]
	v_mov_b64_e32 v[14:15], v[62:63]
	v_lshl_add_u64 v[232:233], s[36:37], 0, v[146:147]
	v_lshl_add_u64 v[234:235], s[36:37], 0, v[142:143]
	global_load_dwordx4 v[118:121], v[232:233], off
	global_load_dwordx4 v[114:117], v[234:235], off
	v_lshl_add_u64 v[232:233], s[36:37], 0, v[144:145]
	v_lshl_add_u64 v[234:235], s[36:37], 0, v[140:141]
	global_load_dwordx4 v[126:129], v[232:233], off
	global_load_dwordx4 v[122:125], v[234:235], off
	s_waitcnt lgkmcnt(0)
	s_barrier
	s_branch .LBB0_1433
; #define LAS __attribute__((address_space(3)))
; DI unsigned pk2(float lo, float hi) { f32x2 v = {lo, hi}; bf16x2_t b = __builtin_convertvector(v, bf16x2_t); return __builtin_bit_cast(unsigned, b); }
; #define MFMA32(a, b, c) __builtin_amdgcn_mfma_f32_32x32x16_bf16((a), (b), (c), 0, 0, 0)
; template <int NK32>
; DI void attn_tile(const LAS unsigned char* Kb, const LAS unsigned char* Vb, int map, int lane, const bf16x8 (&Q)[4], f32x16 (&O)[4], float& m, float& l) {
;     ...
;     float ps = 0.f;
; #pragma unroll
;     for (int kt = 0; kt < NK32; ++kt)
; #pragma unroll
;         for (int i = 0; i < 16; ++i) { const float p = __builtin_amdgcn_exp2f(S[kt][i] - m); S[kt][i] = p; ps += p; }
;     l += ps;
; #pragma unroll
;     for (int sl = 0; sl < 2 * NK32; ++sl) {
;         const int kt = sl >> 1, r0 = 8 * (sl & 1);
;         v4u pu; pu.x = pk2(S[kt][r0 + 0], S[kt][r0 + 1]); pu.y = pk2(S[kt][r0 + 2], S[kt][r0 + 3]); pu.z = pk2(S[kt][r0 + 4], S[kt][r0 + 5]); pu.w = pk2(S[kt][r0 + 6], S[kt][r0 + 7]);
;         const bf16x8 pf = __builtin_bit_cast(bf16x8, pu);
; #pragma unroll
;         for (int dt = 0; dt < 4; ++dt) {
;             const bf16x8 vf = *(const LAS bf16x8*)(Vb + (dt * 32 + r32) * 144 + sl * 32 + hf * 16);
;             O[dt] = MFMA32(vf, pf, O[dt]);
;         }
;     }
; DI void attn_prompt_item(const __attribute__((address_space(4))) Args& a, LAS unsigned char* lds, int ws_, int b, int h, int qt, float lam, bool dry = false) {
;     ...
;     for (int kt = 0; kt < nt; ++kt) {
;         const bool more = kt + 1 < nt;
;         if (more) {
; #pragma unroll
;             for (int i = 0; i < 2; ++i) { kx[i] = *(const v4u*)(ksrc[i] + (size_t)(kt + 1) * 64 * 1024); vx[i] = *(const v4u*)(vsrc[i] + (kt + 1) * 64); }
;         }
;         const LAS unsigned char* buf = lds + (kt & 1) * KV_BYTES;
;         if (kt < my_nt) attn_tile<2>(buf, buf + KT_BYTES, map, lane, Q, O, m, l);
;         if (more) {
;             LAS unsigned char* nb = lds + ((kt + 1) & 1) * KV_BYTES;
; #pragma unroll
;             for (int i = 0; i < 2; ++i) { *(LAS v4u*)(nb + kdst[i]) = kx[i]; *(LAS v4u*)(nb + vdst[i]) = vx[i]; }
;         }
.LBB0_1431:
	s_sub_i32 s11, 0x8c00, s10
	v_add_u32_e32 v210, s11, v132
	v_add_u32_e32 v211, s11, v134
	v_add_u32_e32 v212, s11, v136
	v_add_u32_e32 v213, s11, v138
	ds_read_b128 v[232:235], v253 offset:17440
	ds_read_b128 v[236:239], v254 offset:17440
	ds_read_b128 v[240:243], v253 offset:26656
	ds_read_b128 v[244:247], v252 offset:17440
	s_waitcnt lgkmcnt(4)
	v_mfma_f32_32x32x16_bf16 v[48:63], v[214:217], v[164:167], v[48:63]
	v_exp_f32_e32 v156, v88
	v_exp_f32_e32 v157, v89
	v_exp_f32_e32 v158, v90
	v_exp_f32_e32 v159, v91
	v_add_f32_e32 v168, v156, v168
	v_mfma_f32_32x32x16_bf16 v[32:47], v[218:221], v[164:167], v[32:47]
	v_exp_f32_e32 v160, v92
	v_exp_f32_e32 v161, v93
	v_add_f32_e32 v169, v157, v169
	v_add_f32_e32 v168, v158, v168
	v_cvt_pk_bf16_f32 v176, v156, v157
	v_mfma_f32_32x32x16_bf16 v[16:31], v[222:225], v[164:167], v[16:31]
	v_exp_f32_e32 v162, v94
	v_exp_f32_e32 v163, v95
	v_add_f32_e32 v169, v159, v169
	v_add_f32_e32 v168, v160, v168
	v_cvt_pk_bf16_f32 v177, v158, v159
	v_mfma_f32_32x32x16_bf16 v[0:15], v[226:229], v[164:167], v[0:15]
	s_waitcnt vmcnt(3)
	ds_write_b128 v210, v[118:121]
	ds_read_b128 v[214:217], v253 offset:17472
	ds_read_b128 v[218:221], v254 offset:17472
	ds_read_b128 v[222:225], v253 offset:26688
	ds_read_b128 v[226:229], v252 offset:17472
	v_cvt_pk_bf16_f32 v178, v160, v161
	v_cvt_pk_bf16_f32 v179, v162, v163
	v_add_f32_e32 v169, v161, v169
	v_add_f32_e32 v168, v162, v168
	v_add_f32_e32 v169, v163, v169
	s_waitcnt lgkmcnt(5)
	v_mfma_f32_32x32x16_bf16 v[48:63], v[232:235], v[176:179], v[48:63]
	v_exp_f32_e32 v156, v64
	v_exp_f32_e32 v157, v65
	v_exp_f32_e32 v158, v66
	v_exp_f32_e32 v159, v67
	v_add_f32_e32 v168, v156, v168
	v_mfma_f32_32x32x16_bf16 v[32:47], v[236:239], v[176:179], v[32:47]
	v_exp_f32_e32 v160, v68
	v_exp_f32_e32 v161, v69
	v_add_f32_e32 v169, v157, v169
	v_add_f32_e32 v168, v158, v168
	v_cvt_pk_bf16_f32 v164, v156, v157
	v_mfma_f32_32x32x16_bf16 v[16:31], v[240:243], v[176:179], v[16:31]
	s_waitcnt vmcnt(2)
	ds_write_b128 v211, v[114:117] offset:17408
	v_exp_f32_e32 v162, v70
	v_exp_f32_e32 v163, v71
	v_add_f32_e32 v169, v159, v169
	v_add_f32_e32 v168, v160, v168
	v_cvt_pk_bf16_f32 v165, v158, v159
	v_mfma_f32_32x32x16_bf16 v[0:15], v[244:247], v[176:179], v[0:15]
	ds_read_b128 v[232:235], v253 offset:17504
	ds_read_b128 v[236:239], v254 offset:17504
	ds_read_b128 v[240:243], v253 offset:26720
	ds_read_b128 v[244:247], v252 offset:17504
	v_cvt_pk_bf16_f32 v166, v160, v161
	v_cvt_pk_bf16_f32 v167, v162, v163
	v_add_f32_e32 v169, v161, v169
	v_add_f32_e32 v168, v162, v168
	v_add_f32_e32 v169, v163, v169
	s_waitcnt lgkmcnt(5)
	v_mfma_f32_32x32x16_bf16 v[48:63], v[214:217], v[164:167], v[48:63]
	v_exp_f32_e32 v156, v72
	v_exp_f32_e32 v157, v73
	v_exp_f32_e32 v158, v74
	v_exp_f32_e32 v159, v75
	v_add_f32_e32 v168, v156, v168
	v_mfma_f32_32x32x16_bf16 v[32:47], v[218:221], v[164:167], v[32:47]
	s_waitcnt vmcnt(1)
	ds_write_b128 v212, v[126:129]
	v_exp_f32_e32 v160, v76
	v_exp_f32_e32 v161, v77
	v_add_f32_e32 v169, v157, v169
	v_add_f32_e32 v168, v158, v168
	v_cvt_pk_bf16_f32 v176, v156, v157
	v_mfma_f32_32x32x16_bf16 v[16:31], v[222:225], v[164:167], v[16:31]
	v_exp_f32_e32 v162, v78
	v_exp_f32_e32 v163, v79
	v_add_f32_e32 v169, v159, v169
	v_add_f32_e32 v168, v160, v168
	v_cvt_pk_bf16_f32 v177, v158, v159
	v_mfma_f32_32x32x16_bf16 v[0:15], v[226:229], v[164:167], v[0:15]
	v_cvt_pk_bf16_f32 v178, v160, v161
	v_cvt_pk_bf16_f32 v179, v162, v163
	v_add_f32_e32 v169, v161, v169
	v_add_f32_e32 v168, v162, v168
	v_add_f32_e32 v169, v163, v169
	s_waitcnt lgkmcnt(1)
	v_mfma_f32_32x32x16_bf16 v[48:63], v[232:235], v[176:179], v[48:63]
	s_waitcnt vmcnt(0)
	ds_write_b128 v213, v[122:125] offset:17408
	v_mfma_f32_32x32x16_bf16 v[32:47], v[236:239], v[176:179], v[32:47]
	v_mfma_f32_32x32x16_bf16 v[16:31], v[240:243], v[176:179], v[16:31]
	v_mfma_f32_32x32x16_bf16 v[0:15], v[244:247], v[176:179], v[0:15]
	v_add_f32_e32 v168, v168, v169
	v_add_f32_e32 v133, v133, v168
	v_cmp_lt_f32_e32 vcc, 0x46000000, v168
	s_cbranch_vccnz .Lpost_resc
.Lpost_back:
	s_add_i32 s9, s9, 1
	s_bitcmp1_b32 s9, 0
	s_cselect_b32 s10, 0x8c00, 0
	v_lshl_add_u64 v[140:141], v[140:141], 0, s[28:29]
	v_lshl_add_u64 v[142:143], v[142:143], 0, s[28:29]
	v_lshl_add_u64 v[144:145], v[144:145], 0, s[30:31]
	s_cmp_eq_u32 s8, s9
	v_lshl_add_u64 v[146:147], v[146:147], 0, s[30:31]
	s_cbranch_scc1 .Lnold_a
	v_lshl_add_u64 v[228:229], s[36:37], 0, v[146:147]
	v_lshl_add_u64 v[230:231], s[36:37], 0, v[142:143]
	global_load_dwordx4 v[118:121], v[228:229], off
	global_load_dwordx4 v[114:117], v[230:231], off
	v_lshl_add_u64 v[228:229], s[36:37], 0, v[144:145]
	v_lshl_add_u64 v[230:231], s[36:37], 0, v[140:141]
	global_load_dwordx4 v[126:129], v[228:229], off
	global_load_dwordx4 v[122:125], v[230:231], off

; #define LAS __attribute__((address_space(3)))
; DI float half_max(float v) { auto rr = __builtin_amdgcn_permlane32_swap(__float_as_uint(v), __float_as_uint(v), false, false); return fmaxf(__uint_as_float(rr[0]), __uint_as_float(rr[1])); }
; #define MFMA32(a, b, c) __builtin_amdgcn_mfma_f32_32x32x16_bf16((a), (b), (c), 0, 0, 0)
; template <int NK32>
; DI void attn_tile(const LAS unsigned char* Kb, const LAS unsigned char* Vb, int map, int lane, const bf16x8 (&Q)[4], f32x16 (&O)[4], float& m, float& l) {
;     ...
;     __builtin_amdgcn_s_setprio(1);
; #pragma unroll
;     for (int kt = 0; kt < NK32; ++kt) {
; #pragma unroll
;         for (int i = 0; i < 16; ++i) S[kt][i] = 0.f;
; #pragma unroll
;         for (int ds = 0; ds < 4; ++ds) {
;             const bf16x8 kf = *(const LAS bf16x8*)(Kb + (kt * 32 + r32) * 272 + map * 128 + ds * 32 + hf * 16);
;             S[kt] = MFMA32(kf, Q[ds], S[kt]);
;         }
;     }
;     __builtin_amdgcn_s_setprio(0);
;     float mx = fmaxf(S[0][0], S[0][1]);
; #pragma unroll
;     for (int kt = 0; kt < NK32; ++kt)
; #pragma unroll
;         for (int i = (kt == 0 ? 2 : 0); i < 16; i += 2) mx = fmaxf(fmaxf(mx, S[kt][i]), S[kt][i + 1]);
;     mx = half_max(mx);
;     if (__any(mx > m + 8.f)) {
;         const float mn = fmaxf(m, mx);
;         const float alpha = __builtin_amdgcn_exp2f(m - mn);
;         m = mn; l *= alpha;
; #pragma unroll
;         for (int dt = 0; dt < 4; ++dt)
; #pragma unroll
;             for (int i = 0; i < 16; ++i) O[dt][i] *= alpha;
;     }
;     float ps = 0.f;
; #pragma unroll
;     for (int kt = 0; kt < NK32; ++kt)
; #pragma unroll
;         for (int i = 0; i < 16; ++i) { const float p = __builtin_amdgcn_exp2f(S[kt][i] - m); S[kt][i] = p; ps += p; }
;     l += ps;
.LBB0_1433:
	s_cmp_ge_u32 s9, s7
	s_cbranch_scc1 .LBB0_1432
	s_bitcmp1_b32 s9, 0
	s_cselect_b32 s10, 0x8c00, 0
	s_add_i32 s10, s10, 0
	s_setprio 1
	s_add_i32 s11, s10, s89
	v_add_u32_e32 v72, s11, v130
	v_add_u32_e32 v73, v72, v153
	v_add_u32_e32 v155, v72, v154
	ds_read_b128 v[64:67], v73
	ds_read_b128 v[68:71], v73 offset:32
	ds_read_b128 v[232:235], v73 offset:64
	ds_read_b128 v[236:239], v73 offset:96
	ds_read_b128 v[240:243], v155
	ds_read_b128 v[244:247], v155 offset:32
	ds_read_b128 v[248:251], v155 offset:64
	ds_read_b128 v[184:187], v155 offset:96
	s_waitcnt vmcnt(7) lgkmcnt(7)
	v_mfma_f32_32x32x16_bf16 v[80:95], v[64:67], v[110:113], v[192:207]
	s_waitcnt vmcnt(6) lgkmcnt(6)
	v_mfma_f32_32x32x16_bf16 v[80:95], v[68:71], v[106:109], v[80:95]
	s_waitcnt vmcnt(5) lgkmcnt(5)
	v_mfma_f32_32x32x16_bf16 v[80:95], v[232:235], v[102:105], v[80:95]
	s_waitcnt vmcnt(4) lgkmcnt(4)
	v_mfma_f32_32x32x16_bf16 v[80:95], v[236:239], v[98:101], v[80:95]
	s_waitcnt lgkmcnt(3)
	v_mfma_f32_32x32x16_bf16 v[64:79], v[240:243], v[110:113], v[192:207]
	s_waitcnt lgkmcnt(2)
	v_mfma_f32_32x32x16_bf16 v[64:79], v[244:247], v[106:109], v[64:79]
	v_add_u32_e32 v252, s10, v130
	v_add_u32_e32 v253, v252, v139
	v_add_u32_e32 v254, v252, v137
	v_add_u32_e32 v252, v252, v135
	ds_read_b128 v[214:217], v253 offset:17408
	ds_read_b128 v[218:221], v254 offset:17408
	ds_read_b128 v[222:225], v253 offset:26624
	ds_read_b128 v[226:229], v252 offset:17408
	v_mov_b32_e32 v168, 0
	v_mov_b32_e32 v169, 0
	v_exp_f32_e32 v156, v80
	v_exp_f32_e32 v157, v81
	v_exp_f32_e32 v158, v82
	v_exp_f32_e32 v159, v83
	v_add_f32_e32 v168, v156, v168
	v_exp_f32_e32 v160, v84
	v_exp_f32_e32 v161, v85
	v_add_f32_e32 v169, v157, v169
	v_add_f32_e32 v168, v158, v168
	v_cvt_pk_bf16_f32 v164, v156, v157
	s_waitcnt lgkmcnt(5)
	v_mfma_f32_32x32x16_bf16 v[64:79], v[248:251], v[102:105], v[64:79]
	v_exp_f32_e32 v162, v86
	v_exp_f32_e32 v163, v87
	v_add_f32_e32 v169, v159, v169
	v_add_f32_e32 v168, v160, v168
	v_cvt_pk_bf16_f32 v165, v158, v159
	v_cvt_pk_bf16_f32 v166, v160, v161
	v_cvt_pk_bf16_f32 v167, v162, v163
	v_add_f32_e32 v169, v161, v169
	v_add_f32_e32 v168, v162, v168
	v_add_f32_e32 v169, v163, v169
	s_waitcnt lgkmcnt(4)
	v_mfma_f32_32x32x16_bf16 v[64:79], v[184:187], v[98:101], v[64:79]
	s_setprio 0
	s_branch .LBB0_1431
.Lpost_resc:
	v_mov_b32_e32 v155, v168
	s_nop 1
	v_permlane32_swap_b32_e32 v168, v155
	v_add_f32_e32 v155, v168, v155
	v_max_f32_e32 v155, 1.0, v155
	v_log_f32_e32 v157, v155
	s_nop 0
	v_ceil_f32_e32 v157, v157
	v_sub_f32_e32 v192, v192, v157
	v_mul_f32_e32 v156, -1.0, v157
	v_exp_f32_e32 v156, v156
	v_mov_b32_e32 v193, v192
	v_mov_b32_e32 v194, v192
	v_mov_b32_e32 v195, v192
	v_mov_b32_e32 v196, v192
	v_mov_b32_e32 v197, v192
	v_mov_b32_e32 v198, v192
	v_mov_b32_e32 v199, v192
	v_mov_b32_e32 v200, v192
	v_mov_b32_e32 v201, v192
	v_mov_b32_e32 v202, v192
	v_mov_b32_e32 v203, v192
	v_mov_b32_e32 v204, v192
	v_mov_b32_e32 v205, v192
	v_mov_b32_e32 v206, v192
	v_mov_b32_e32 v207, v192
	v_mul_f32_e32 v133, v133, v156
	v_pk_mul_f32 v[62:63], v[62:63], v[156:157] op_sel_hi:[1,0]
	v_pk_mul_f32 v[60:61], v[60:61], v[156:157] op_sel_hi:[1,0]
	v_pk_mul_f32 v[58:59], v[58:59], v[156:157] op_sel_hi:[1,0]
	v_pk_mul_f32 v[56:57], v[56:57], v[156:157] op_sel_hi:[1,0]
	v_pk_mul_f32 v[54:55], v[54:55], v[156:157] op_sel_hi:[1,0]
	v_pk_mul_f32 v[52:53], v[52:53], v[156:157] op_sel_hi:[1,0]
	v_pk_mul_f32 v[50:51], v[50:51], v[156:157] op_sel_hi:[1,0]
	v_pk_mul_f32 v[48:49], v[48:49], v[156:157] op_sel_hi:[1,0]
	v_pk_mul_f32 v[46:47], v[46:47], v[156:157] op_sel_hi:[1,0]
	v_pk_mul_f32 v[44:45], v[44:45], v[156:157] op_sel_hi:[1,0]
	v_pk_mul_f32 v[42:43], v[42:43], v[156:157] op_sel_hi:[1,0]
	v_pk_mul_f32 v[40:41], v[40:41], v[156:157] op_sel_hi:[1,0]
	v_pk_mul_f32 v[38:39], v[38:39], v[156:157] op_sel_hi:[1,0]
	v_pk_mul_f32 v[36:37], v[36:37], v[156:157] op_sel_hi:[1,0]
	v_pk_mul_f32 v[34:35], v[34:35], v[156:157] op_sel_hi:[1,0]
	v_pk_mul_f32 v[32:33], v[32:33], v[156:157] op_sel_hi:[1,0]
	v_pk_mul_f32 v[30:31], v[30:31], v[156:157] op_sel_hi:[1,0]
	v_pk_mul_f32 v[28:29], v[28:29], v[156:157] op_sel_hi:[1,0]
	v_pk_mul_f32 v[26:27], v[26:27], v[156:157] op_sel_hi:[1,0]
	v_pk_mul_f32 v[24:25], v[24:25], v[156:157] op_sel_hi:[1,0]
	v_pk_mul_f32 v[22:23], v[22:23], v[156:157] op_sel_hi:[1,0]
	v_pk_mul_f32 v[20:21], v[20:21], v[156:157] op_sel_hi:[1,0]
	v_pk_mul_f32 v[18:19], v[18:19], v[156:157] op_sel_hi:[1,0]
	v_pk_mul_f32 v[16:17], v[16:17], v[156:157] op_sel_hi:[1,0]
	v_pk_mul_f32 v[14:15], v[14:15], v[156:157] op_sel_hi:[1,0]
	v_pk_mul_f32 v[12:13], v[12:13], v[156:157] op_sel_hi:[1,0]
	v_pk_mul_f32 v[10:11], v[10:11], v[156:157] op_sel_hi:[1,0]
	v_pk_mul_f32 v[8:9], v[8:9], v[156:157] op_sel_hi:[1,0]
	v_pk_mul_f32 v[6:7], v[6:7], v[156:157] op_sel_hi:[1,0]
	v_pk_mul_f32 v[4:5], v[4:5], v[156:157] op_sel_hi:[1,0]
	v_pk_mul_f32 v[2:3], v[2:3], v[156:157] op_sel_hi:[1,0]
	v_pk_mul_f32 v[0:1], v[0:1], v[156:157] op_sel_hi:[1,0]
	s_branch .Lpost_back
